# v44 + LN1/LN2 phases: all 32 row loads issued together, gain/bias/shift/scale loads issued under the reductions (de-serialised)
# speedup vs baseline: 1.0058x; 1.0058x over previous
; #define GAS __attribute__((address_space(1)))
; __device__ __forceinline__ f32x4 ldx4(const GAS f16_t* p) { const f16x4 h = *(const GAS f16x4*)p; return __builtin_convertvector(h, f32x4); }
; __device__ __forceinline__ void ln_phase(Frame& F, CArgs a, int l, int which) {
;     ...
;     for (int base = 0; base < 1024; base += 4 * F.G) {
;         const int rr = base + p * F.G + F.blk; const bool valid = rr < 1024; const int row = 8192 + (valid ? rr : 0);
;         const GAS f32x4* sr = (const GAS f32x4*)(S + (size_t)row * D);
;         f32x4 v[4]; float s = 0.f;
; #pragma unroll
;         for (int j = 0; j < 4; ++j) {
;             const int i4 = lane + 64 * (j + 4 * half);
;             f32x4 t8[8]; t8[0] = sr[i4];
; #pragma unroll
;             for (int q = 0; q < 7; ++q) t8[q + 1] = ldx4(PBp + ((size_t)q * 1024 + (row - 8192)) * D + i4 * 4);
;             v[j] = ((t8[0] + t8[1]) + (t8[2] + t8[3])) + ((t8[4] + t8[5]) + (t8[6] + t8[7]));
;             s += (v[j][0] + v[j][1]) + (v[j][2] + v[j][3]); }
.LBB0_1420:
	s_add_i32 s12, s23, s18
	s_cmpk_lt_i32 s12, 0x400
	s_cselect_b64 s[10:11], -1, 0
	s_and_b64 s[8:9], s[10:11], exec
	s_cselect_b32 s12, s12, 0
	s_add_i32 s8, s12, 0x2000
	s_ashr_i32 s9, s8, 31
	s_ashr_i32 s13, s12, 31
	s_lshl_b64 s[12:13], s[12:13], 12
	s_lshl_b64 s[24:25], s[8:9], 13
	v_lshl_add_u64 v[62:63], v[42:43], 0, s[24:25]
	s_load_dwordx2 s[100:101], s[0:1], 0x130
	s_waitcnt lgkmcnt(0)
	s_add_u32 s100, s100, 0x46000000
	s_addc_u32 s101, s101, 0
	s_add_u32 s100, s100, s12
	s_addc_u32 s101, s101, s13
	v_lshlrev_b32_e32 v172, 1, v6
	v_lshlrev_b32_e32 v173, 1, v10
	v_lshlrev_b32_e32 v174, 1, v14
	v_lshlrev_b32_e32 v175, 1, v18
	global_load_dwordx4 v[104:107], v[62:63], off
	global_load_dwordx4 v[122:125], v[62:63], off offset:1024
	global_load_dwordx4 v[140:143], v[62:63], off offset:2048
	global_load_dwordx4 v[156:159], v[62:63], off offset:3072
	global_load_dwordx2 v[100:101], v172, s[100:101]
	global_load_dwordx2 v[118:119], v173, s[100:101]
	global_load_dwordx2 v[138:139], v174, s[100:101]
	global_load_dwordx2 v[148:149], v175, s[100:101]
	s_add_u32 s100, s100, 0x400000
	s_addc_u32 s101, s101, 0
	global_load_dwordx2 v[102:103], v172, s[100:101]
	global_load_dwordx2 v[120:121], v173, s[100:101]
	global_load_dwordx2 v[136:137], v174, s[100:101]
	global_load_dwordx2 v[160:161], v175, s[100:101]
	s_add_u32 s100, s100, 0x400000
	s_addc_u32 s101, s101, 0
	global_load_dwordx2 v[108:109], v172, s[100:101]
	global_load_dwordx2 v[126:127], v173, s[100:101]
	global_load_dwordx2 v[144:145], v174, s[100:101]
	global_load_dwordx2 v[162:163], v175, s[100:101]
	s_add_u32 s100, s100, 0x400000
	s_addc_u32 s101, s101, 0
	global_load_dwordx2 v[110:111], v172, s[100:101]
	global_load_dwordx2 v[128:129], v173, s[100:101]
	global_load_dwordx2 v[146:147], v174, s[100:101]
	global_load_dwordx2 v[164:165], v175, s[100:101]
	s_add_u32 s100, s100, 0x400000
	s_addc_u32 s101, s101, 0
	global_load_dwordx2 v[112:113], v172, s[100:101]
	global_load_dwordx2 v[130:131], v173, s[100:101]
	global_load_dwordx2 v[150:151], v174, s[100:101]
	global_load_dwordx2 v[166:167], v175, s[100:101]
	s_add_u32 s100, s100, 0x400000
	s_addc_u32 s101, s101, 0
	global_load_dwordx2 v[114:115], v172, s[100:101]
	global_load_dwordx2 v[132:133], v173, s[100:101]
	global_load_dwordx2 v[152:153], v174, s[100:101]
	global_load_dwordx2 v[168:169], v175, s[100:101]
	s_add_u32 s100, s100, 0x400000
	s_addc_u32 s101, s101, 0
	global_load_dwordx2 v[116:117], v172, s[100:101]
	global_load_dwordx2 v[134:135], v173, s[100:101]
	global_load_dwordx2 v[154:155], v174, s[100:101]
	global_load_dwordx2 v[170:171], v175, s[100:101]
	s_waitcnt vmcnt(0)
	v_lshl_add_u64 v[46:47], v[8:9], 0, s[12:13]
	s_mov_b32 s24, 0x400000
	v_add_co_u32_e32 v52, vcc, s24, v46
	s_nop 0
	v_addc_co_u32_e32 v53, vcc, 0, v47, vcc
	s_mov_b32 s25, 0x800000
	s_mov_b32 s26, 0xc00000
	s_mov_b32 s27, 0x1000000
	s_mov_b32 s34, 0x1400000
	s_mov_b32 s35, 0x1800000
	v_lshl_add_u64 v[90:91], v[20:21], 0, s[12:13]
	v_cvt_f32_f16_e32 v50, v100
	v_cvt_f32_f16_sdwa v51, v100 dst_sel:DWORD dst_unused:UNUSED_PAD src0_sel:WORD_1
	v_cvt_f32_f16_e32 v48, v101
	v_cvt_f32_f16_e32 v56, v102
	v_cvt_f32_f16_sdwa v57, v102 dst_sel:DWORD dst_unused:UNUSED_PAD src0_sel:WORD_1
	v_add_co_u32_e32 v52, vcc, s25, v46
	v_cvt_f32_f16_e32 v54, v103
	v_cvt_f32_f16_sdwa v55, v103 dst_sel:DWORD dst_unused:UNUSED_PAD src0_sel:WORD_1
	v_addc_co_u32_e32 v53, vcc, 0, v47, vcc
	v_cvt_f32_f16_sdwa v49, v101 dst_sel:DWORD dst_unused:UNUSED_PAD src0_sel:WORD_1
	v_pk_add_f32 v[2:3], v[104:105], v[50:51]
	v_pk_add_f32 v[4:5], v[106:107], v[48:49]
	v_cvt_f32_f16_e32 v60, v108
	v_cvt_f32_f16_sdwa v61, v108 dst_sel:DWORD dst_unused:UNUSED_PAD src0_sel:WORD_1
	v_add_co_u32_e32 v52, vcc, s26, v46
	v_cvt_f32_f16_e32 v58, v109
	v_cvt_f32_f16_sdwa v59, v109 dst_sel:DWORD dst_unused:UNUSED_PAD src0_sel:WORD_1
	v_addc_co_u32_e32 v53, vcc, 0, v47, vcc
	v_pk_add_f32 v[48:49], v[54:55], v[58:59]
	v_cvt_f32_f16_e32 v66, v110
	v_cvt_f32_f16_sdwa v67, v110 dst_sel:DWORD dst_unused:UNUSED_PAD src0_sel:WORD_1
	v_add_co_u32_e32 v52, vcc, s27, v46
	v_cvt_f32_f16_e32 v64, v111
	v_cvt_f32_f16_sdwa v65, v111 dst_sel:DWORD dst_unused:UNUSED_PAD src0_sel:WORD_1
	v_addc_co_u32_e32 v53, vcc, 0, v47, vcc
	v_pk_add_f32 v[4:5], v[4:5], v[48:49]
	v_cvt_f32_f16_e32 v70, v112
	v_cvt_f32_f16_sdwa v71, v112 dst_sel:DWORD dst_unused:UNUSED_PAD src0_sel:WORD_1
	v_add_co_u32_e32 v52, vcc, s34, v46
	v_cvt_f32_f16_e32 v68, v113
	v_cvt_f32_f16_sdwa v69, v113 dst_sel:DWORD dst_unused:UNUSED_PAD src0_sel:WORD_1
	v_addc_co_u32_e32 v53, vcc, 0, v47, vcc
	v_add_co_u32_e32 v46, vcc, s35, v46
	s_nop 0
	v_addc_co_u32_e32 v47, vcc, 0, v47, vcc
	v_pk_add_f32 v[48:49], v[64:65], v[68:69]
	v_cvt_f32_f16_e32 v74, v114
	v_cvt_f32_f16_sdwa v75, v114 dst_sel:DWORD dst_unused:UNUSED_PAD src0_sel:WORD_1
	v_cvt_f32_f16_e32 v72, v115
	v_cvt_f32_f16_e32 v76, v116
	v_cvt_f32_f16_sdwa v77, v116 dst_sel:DWORD dst_unused:UNUSED_PAD src0_sel:WORD_1
	v_cvt_f32_f16_sdwa v73, v115 dst_sel:DWORD dst_unused:UNUSED_PAD src0_sel:WORD_1
	v_cvt_f32_f16_e32 v52, v117
	v_cvt_f32_f16_sdwa v53, v117 dst_sel:DWORD dst_unused:UNUSED_PAD src0_sel:WORD_1
	v_pk_add_f32 v[46:47], v[56:57], v[60:61]
	v_pk_add_f32 v[50:51], v[74:75], v[76:77]
	v_pk_add_f32 v[2:3], v[2:3], v[46:47]
	v_pk_add_f32 v[46:47], v[66:67], v[70:71]
	v_pk_add_f32 v[52:53], v[72:73], v[52:53]
	v_pk_add_f32 v[46:47], v[46:47], v[50:51]
	v_pk_add_f32 v[48:49], v[48:49], v[52:53]
	v_pk_add_f32 v[52:53], v[2:3], v[46:47]
	v_lshl_add_u64 v[46:47], v[12:13], 0, s[12:13]
	v_add_co_u32_e32 v58, vcc, s24, v46
	v_pk_add_f32 v[50:51], v[4:5], v[48:49]
	s_nop 0
	v_addc_co_u32_e32 v59, vcc, 0, v47, vcc
; __device__ __forceinline__ f32x4 ldx4(const GAS f16_t* p) { const f16x4 h = *(const GAS f16x4*)p; return __builtin_convertvector(h, f32x4); }
; __device__ __forceinline__ void ln_phase(Frame& F, CArgs a, int l, int which) {
;     ...
;         for (int j = 0; j < 4; ++j) {
;             const int i4 = lane + 64 * (j + 4 * half);
;             f32x4 t8[8]; t8[0] = sr[i4];
; #pragma unroll
;             for (int q = 0; q < 7; ++q) t8[q + 1] = ldx4(PBp + ((size_t)q * 1024 + (row - 8192)) * D + i4 * 4);
;             v[j] = ((t8[0] + t8[1]) + (t8[2] + t8[3])) + ((t8[4] + t8[5]) + (t8[6] + t8[7]));
;             s += (v[j][0] + v[j][1]) + (v[j][2] + v[j][3]); }
	v_pk_mov_b32 v[2:3], v[52:53], v[50:51] op_sel:[1,0]
	v_mov_b32_e32 v4, v52
	v_mov_b32_e32 v5, v51
	v_pk_add_f32 v[2:3], v[2:3], v[4:5]
	v_cvt_f32_f16_e32 v56, v118
	v_add_f32_e32 v2, v2, v3
	v_cvt_f32_f16_e32 v64, v120
	v_cvt_f32_f16_sdwa v65, v120 dst_sel:DWORD dst_unused:UNUSED_PAD src0_sel:WORD_1
	v_add_co_u32_e32 v58, vcc, s25, v46
	v_cvt_f32_f16_e32 v60, v121
	v_cvt_f32_f16_sdwa v61, v121 dst_sel:DWORD dst_unused:UNUSED_PAD src0_sel:WORD_1
	v_addc_co_u32_e32 v59, vcc, 0, v47, vcc
	v_add_f32_e32 v54, 0, v2
	v_cvt_f32_f16_sdwa v57, v118 dst_sel:DWORD dst_unused:UNUSED_PAD src0_sel:WORD_1
	v_cvt_f32_f16_e32 v48, v119
	v_cvt_f32_f16_sdwa v49, v119 dst_sel:DWORD dst_unused:UNUSED_PAD src0_sel:WORD_1
	v_pk_add_f32 v[2:3], v[122:123], v[56:57]
	v_pk_add_f32 v[4:5], v[124:125], v[48:49]
	v_cvt_f32_f16_e32 v68, v126
	v_cvt_f32_f16_sdwa v69, v126 dst_sel:DWORD dst_unused:UNUSED_PAD src0_sel:WORD_1
	v_add_co_u32_e32 v58, vcc, s26, v46
	v_cvt_f32_f16_e32 v66, v127
	v_cvt_f32_f16_sdwa v67, v127 dst_sel:DWORD dst_unused:UNUSED_PAD src0_sel:WORD_1
	v_addc_co_u32_e32 v59, vcc, 0, v47, vcc
	v_pk_add_f32 v[48:49], v[60:61], v[66:67]
	v_cvt_f32_f16_e32 v72, v128
	v_cvt_f32_f16_sdwa v73, v128 dst_sel:DWORD dst_unused:UNUSED_PAD src0_sel:WORD_1
	v_add_co_u32_e32 v58, vcc, s27, v46
	v_cvt_f32_f16_e32 v70, v129
	v_cvt_f32_f16_sdwa v71, v129 dst_sel:DWORD dst_unused:UNUSED_PAD src0_sel:WORD_1
	v_addc_co_u32_e32 v59, vcc, 0, v47, vcc
	v_pk_add_f32 v[4:5], v[4:5], v[48:49]
	v_cvt_f32_f16_e32 v76, v130
	v_cvt_f32_f16_sdwa v77, v130 dst_sel:DWORD dst_unused:UNUSED_PAD src0_sel:WORD_1
	v_add_co_u32_e32 v58, vcc, s34, v46
	v_cvt_f32_f16_e32 v74, v131
	v_cvt_f32_f16_sdwa v75, v131 dst_sel:DWORD dst_unused:UNUSED_PAD src0_sel:WORD_1
	v_addc_co_u32_e32 v59, vcc, 0, v47, vcc
	v_add_co_u32_e32 v46, vcc, s35, v46
	s_nop 0
	v_addc_co_u32_e32 v47, vcc, 0, v47, vcc
	v_pk_add_f32 v[48:49], v[70:71], v[74:75]
	v_cvt_f32_f16_e32 v80, v132
	v_cvt_f32_f16_sdwa v81, v132 dst_sel:DWORD dst_unused:UNUSED_PAD src0_sel:WORD_1
	v_cvt_f32_f16_e32 v78, v133
	v_cvt_f32_f16_e32 v82, v134
	v_cvt_f32_f16_sdwa v83, v134 dst_sel:DWORD dst_unused:UNUSED_PAD src0_sel:WORD_1
	v_cvt_f32_f16_sdwa v79, v133 dst_sel:DWORD dst_unused:UNUSED_PAD src0_sel:WORD_1
	v_cvt_f32_f16_e32 v58, v135
	v_cvt_f32_f16_sdwa v59, v135 dst_sel:DWORD dst_unused:UNUSED_PAD src0_sel:WORD_1
	v_pk_add_f32 v[46:47], v[64:65], v[68:69]
	v_pk_add_f32 v[56:57], v[80:81], v[82:83]
	v_pk_add_f32 v[2:3], v[2:3], v[46:47]
	v_pk_add_f32 v[46:47], v[72:73], v[76:77]
	v_pk_add_f32 v[58:59], v[78:79], v[58:59]
	v_pk_add_f32 v[46:47], v[46:47], v[56:57]
	v_lshl_add_u64 v[56:57], v[16:17], 0, s[12:13]
	v_add_co_u32_e32 v66, vcc, s24, v56
	v_pk_add_f32 v[58:59], v[48:49], v[58:59]
	s_nop 0
	v_addc_co_u32_e32 v67, vcc, 0, v57, vcc
	v_pk_add_f32 v[48:49], v[2:3], v[46:47]
	v_pk_add_f32 v[46:47], v[4:5], v[58:59]
	v_mov_b32_e32 v4, v48
	v_pk_mov_b32 v[2:3], v[48:49], v[46:47] op_sel:[1,0]
	v_mov_b32_e32 v5, v47
	v_pk_add_f32 v[2:3], v[2:3], v[4:5]
	v_pk_add_f32 v[60:61], v[2:3], v[2:3] op_sel:[0,1] op_sel_hi:[1,0]
	v_cvt_f32_f16_e32 v70, v136
	v_cvt_f32_f16_sdwa v71, v136 dst_sel:DWORD dst_unused:UNUSED_PAD src0_sel:WORD_1
	v_add_co_u32_e32 v66, vcc, s25, v56
	v_cvt_f32_f16_e32 v68, v137
	v_cvt_f32_f16_sdwa v69, v137 dst_sel:DWORD dst_unused:UNUSED_PAD src0_sel:WORD_1
	v_addc_co_u32_e32 v67, vcc, 0, v57, vcc
	v_cvt_f32_f16_e32 v64, v138
	v_cvt_f32_f16_sdwa v65, v138 dst_sel:DWORD dst_unused:UNUSED_PAD src0_sel:WORD_1
	v_cvt_f32_f16_e32 v58, v139
	v_cvt_f32_f16_sdwa v59, v139 dst_sel:DWORD dst_unused:UNUSED_PAD src0_sel:WORD_1
	v_pk_add_f32 v[2:3], v[140:141], v[64:65]
	v_pk_add_f32 v[4:5], v[142:143], v[58:59]
	v_cvt_f32_f16_e32 v74, v144
	v_cvt_f32_f16_sdwa v75, v144 dst_sel:DWORD dst_unused:UNUSED_PAD src0_sel:WORD_1
	v_add_co_u32_e32 v66, vcc, s26, v56
	v_cvt_f32_f16_e32 v72, v145
	v_cvt_f32_f16_sdwa v73, v145 dst_sel:DWORD dst_unused:UNUSED_PAD src0_sel:WORD_1
	v_addc_co_u32_e32 v67, vcc, 0, v57, vcc
	v_pk_add_f32 v[58:59], v[68:69], v[72:73]
	v_pk_add_f32 v[4:5], v[4:5], v[58:59]
	v_cvt_f32_f16_e32 v78, v146
	v_cvt_f32_f16_sdwa v79, v146 dst_sel:DWORD dst_unused:UNUSED_PAD src0_sel:WORD_1
	v_add_co_u32_e32 v66, vcc, s27, v56
	v_cvt_f32_f16_e32 v76, v147
	v_cvt_f32_f16_sdwa v77, v147 dst_sel:DWORD dst_unused:UNUSED_PAD src0_sel:WORD_1
	v_addc_co_u32_e32 v67, vcc, 0, v57, vcc
	v_cvt_f32_f16_e32 v82, v150
	v_cvt_f32_f16_sdwa v83, v150 dst_sel:DWORD dst_unused:UNUSED_PAD src0_sel:WORD_1
	v_add_co_u32_e32 v66, vcc, s34, v56
	v_cvt_f32_f16_e32 v80, v151
	v_cvt_f32_f16_sdwa v81, v151 dst_sel:DWORD dst_unused:UNUSED_PAD src0_sel:WORD_1
	v_addc_co_u32_e32 v67, vcc, 0, v57, vcc
	v_add_co_u32_e32 v56, vcc, s35, v56
	s_nop 0
	v_addc_co_u32_e32 v57, vcc, 0, v57, vcc
	v_pk_add_f32 v[58:59], v[76:77], v[80:81]
	v_cvt_f32_f16_e32 v84, v153
	v_cvt_f32_f16_sdwa v85, v153 dst_sel:DWORD dst_unused:UNUSED_PAD src0_sel:WORD_1
	v_cvt_f32_f16_e32 v86, v152
	v_cvt_f32_f16_sdwa v87, v152 dst_sel:DWORD dst_unused:UNUSED_PAD src0_sel:WORD_1
	v_cvt_f32_f16_e32 v66, v155
	v_cvt_f32_f16_sdwa v67, v155 dst_sel:DWORD dst_unused:UNUSED_PAD src0_sel:WORD_1
	v_cvt_f32_f16_e32 v88, v154
	v_cvt_f32_f16_sdwa v89, v154 dst_sel:DWORD dst_unused:UNUSED_PAD src0_sel:WORD_1
	v_pk_add_f32 v[56:57], v[70:71], v[74:75]
	v_add_co_u32_e32 v70, vcc, s24, v90
	v_pk_add_f32 v[2:3], v[2:3], v[56:57]
	s_nop 0
	v_addc_co_u32_e32 v71, vcc, 0, v91, vcc
	v_add_co_u32_e32 v74, vcc, s25, v90
	v_pk_add_f32 v[56:57], v[78:79], v[82:83]
	s_nop 0
	v_addc_co_u32_e32 v75, vcc, 0, v91, vcc
	v_add_co_u32_e32 v78, vcc, s26, v90
	v_pk_add_f32 v[64:65], v[86:87], v[88:89]
	s_nop 0
	v_addc_co_u32_e32 v79, vcc, 0, v91, vcc
	v_add_co_u32_e32 v82, vcc, s27, v90
	v_pk_add_f32 v[66:67], v[84:85], v[66:67]
	s_nop 0
	v_addc_co_u32_e32 v83, vcc, 0, v91, vcc
	v_add_co_u32_e32 v86, vcc, s34, v90
	v_pk_add_f32 v[66:67], v[58:59], v[66:67]
	s_nop 0
	v_addc_co_u32_e32 v87, vcc, 0, v91, vcc
	v_pk_add_f32 v[56:57], v[56:57], v[64:65]
	v_add_co_u32_e32 v90, vcc, s35, v90
	v_pk_add_f32 v[58:59], v[2:3], v[56:57]
	v_pk_add_f32 v[56:57], v[4:5], v[66:67]
	v_addc_co_u32_e32 v91, vcc, 0, v91, vcc
	v_cvt_f32_f16_e32 v62, v148
	v_cvt_f32_f16_sdwa v63, v148 dst_sel:DWORD dst_unused:UNUSED_PAD src0_sel:WORD_1
	v_cvt_f32_f16_e32 v68, v149
	v_cvt_f32_f16_sdwa v69, v149 dst_sel:DWORD dst_unused:UNUSED_PAD src0_sel:WORD_1
	v_add_f32_e32 v64, v58, v59
	v_add_f32_e32 v66, v56, v57
	s_barrier
; #define GAS __attribute__((address_space(1)))
; __device__ __forceinline__ unsigned pk2(float lo, float hi) { unsigned r; asm("v_cvt_pk_bf16_f32 %0, %1, %2" : "=v"(r) : "v"(lo), "v"(hi)); return r; }
; __device__ __forceinline__ void ln_phase(Frame& F, CArgs a, int l, int which) {
;     ...
;             v[j] = ((t8[0] + t8[1]) + (t8[2] + t8[3])) + ((t8[4] + t8[5]) + (t8[6] + t8[7]));
;             s += (v[j][0] + v[j][1]) + (v[j][2] + v[j][3]); }
;         const float mh = wave_sum(s) * (1.0f / 1024.0f); float q = 0.f;
; #pragma unroll
;         for (int j = 0; j < 4; ++j) { const f32x4 d = v[j] - mh; q += (d[0] * d[0] + d[1] * d[1]) + (d[2] * d[2] + d[3] * d[3]); }
;         q = wave_sum(q);
;         __syncthreads();
;         if (lane == 0) XS[F.wave] = (f32x2v){mh, q};
;     ...
;         for (int j = 0; j < 4; ++j) { const int i4 = lane + 64 * (j + 4 * half); const f32x4 y = (v[j] - mean) * rstd * ((const GAS f32x4*)g)[i4] + ((const GAS f32x4*)bb)[i4];
;             stx4(xo + i4 * 4, y);
;             const f32x4 r = y * (((const GAS f32x4*)sc)[i4] + 1.0f) + ((const GAS f32x4*)sh)[i4]; u32x2 w; w.x = pk2(r[0], r[1]); w.y = pk2(r[2], r[3]); xm[i4] = w; }
	v_pk_add_f32 v[4:5], v[158:159], v[68:69]
	v_cvt_f32_f16_e32 v70, v160
	v_cvt_f32_f16_sdwa v71, v160 dst_sel:DWORD dst_unused:UNUSED_PAD src0_sel:WORD_1
	v_cvt_f32_f16_e32 v72, v161
	v_cvt_f32_f16_sdwa v73, v161 dst_sel:DWORD dst_unused:UNUSED_PAD src0_sel:WORD_1
	v_cvt_f32_f16_e32 v74, v162
	v_cvt_f32_f16_sdwa v75, v162 dst_sel:DWORD dst_unused:UNUSED_PAD src0_sel:WORD_1
	v_cvt_f32_f16_e32 v76, v163
	v_cvt_f32_f16_sdwa v77, v163 dst_sel:DWORD dst_unused:UNUSED_PAD src0_sel:WORD_1
	v_cvt_f32_f16_e32 v78, v164
	v_cvt_f32_f16_sdwa v79, v164 dst_sel:DWORD dst_unused:UNUSED_PAD src0_sel:WORD_1
	v_cvt_f32_f16_e32 v80, v165
	v_cvt_f32_f16_sdwa v81, v165 dst_sel:DWORD dst_unused:UNUSED_PAD src0_sel:WORD_1
	v_cvt_f32_f16_e32 v82, v166
	v_cvt_f32_f16_sdwa v83, v166 dst_sel:DWORD dst_unused:UNUSED_PAD src0_sel:WORD_1
	v_cvt_f32_f16_e32 v84, v167
	v_cvt_f32_f16_sdwa v85, v167 dst_sel:DWORD dst_unused:UNUSED_PAD src0_sel:WORD_1
	v_cvt_f32_f16_e32 v86, v168
	v_cvt_f32_f16_sdwa v87, v168 dst_sel:DWORD dst_unused:UNUSED_PAD src0_sel:WORD_1
	v_cvt_f32_f16_e32 v88, v169
	v_cvt_f32_f16_sdwa v89, v169 dst_sel:DWORD dst_unused:UNUSED_PAD src0_sel:WORD_1
	v_cvt_f32_f16_e32 v98, v170
	v_cvt_f32_f16_sdwa v99, v170 dst_sel:DWORD dst_unused:UNUSED_PAD src0_sel:WORD_1
	v_cvt_f32_f16_e32 v90, v171
	v_cvt_f32_f16_sdwa v91, v171 dst_sel:DWORD dst_unused:UNUSED_PAD src0_sel:WORD_1
	v_pk_add_f32 v[2:3], v[156:157], v[62:63]
	global_load_dwordx4 v[100:103], v[22:23], off
	global_load_dwordx4 v[104:107], v[24:25], off
	global_load_dwordx4 v[108:111], v[26:27], off
	global_load_dwordx4 v[112:115], v[28:29], off
	global_load_dwordx4 v[116:119], v[22:23], off offset:1024
	global_load_dwordx4 v[120:123], v[24:25], off offset:1024
	global_load_dwordx4 v[124:127], v[30:31], off
	global_load_dwordx4 v[128:131], v[32:33], off
	global_load_dwordx4 v[132:135], v[22:23], off offset:2048
	global_load_dwordx4 v[136:139], v[24:25], off offset:2048
	global_load_dwordx4 v[140:143], v[34:35], off
	global_load_dwordx4 v[144:147], v[36:37], off
	global_load_dwordx4 v[148:151], v[22:23], off offset:3072
	global_load_dwordx4 v[152:155], v[24:25], off offset:3072
	global_load_dwordx4 v[156:159], v[38:39], off
	global_load_dwordx4 v[160:163], v[40:41], off
	v_pk_add_f32 v[62:63], v[72:73], v[76:77]
	v_pk_add_f32 v[68:69], v[70:71], v[74:75]
	v_pk_add_f32 v[70:71], v[88:89], v[90:91]
	v_pk_add_f32 v[68:69], v[2:3], v[68:69]
	v_pk_add_f32 v[2:3], v[4:5], v[62:63]
	v_pk_add_f32 v[4:5], v[80:81], v[84:85]
	v_pk_add_f32 v[62:63], v[78:79], v[82:83]
	v_pk_add_f32 v[72:73], v[86:87], v[98:99]
	v_pk_add_f32 v[4:5], v[4:5], v[70:71]
	v_pk_add_f32 v[62:63], v[62:63], v[72:73]
	v_pk_add_f32 v[2:3], v[2:3], v[4:5]
	v_pk_add_f32 v[4:5], v[68:69], v[62:63]
	v_mov_b32_e32 v65, v2
	v_mov_b32_e32 v55, v4
	v_mov_b32_e32 v61, v5
	v_mov_b32_e32 v67, v3
	v_pk_add_f32 v[54:55], v[54:55], v[60:61]
	v_pk_add_f32 v[60:61], v[64:65], v[66:67]
	s_nop 0
	v_pk_add_f32 v[54:55], v[54:55], v[60:61]
	s_nop 0
	v_add_f32_e32 v54, v54, v55
	ds_bpermute_b32 v55, v1, v54
	s_waitcnt lgkmcnt(0)
	v_add_f32_e32 v54, v54, v55
	ds_bpermute_b32 v55, v92, v54
	s_waitcnt lgkmcnt(0)
	v_add_f32_e32 v54, v54, v55
	ds_bpermute_b32 v55, v93, v54
	s_waitcnt lgkmcnt(0)
	v_add_f32_e32 v54, v54, v55
	ds_bpermute_b32 v55, v94, v54
	s_waitcnt lgkmcnt(0)
	v_add_f32_e32 v54, v54, v55
	ds_bpermute_b32 v55, v95, v54
	s_waitcnt lgkmcnt(0)
	v_add_f32_e32 v54, v54, v55
	ds_bpermute_b32 v55, v96, v54
	s_waitcnt lgkmcnt(0)
	v_add_f32_e32 v54, v54, v55
	v_fmamk_f32 v60, v54, 0xba800000, v51
	v_fmamk_f32 v62, v54, 0xba800000, v53
	v_fmamk_f32 v55, v54, 0xba800000, v50
	v_fmamk_f32 v61, v54, 0xba800000, v52
	v_mul_f32_e32 v62, v62, v62
	v_mul_f32_e32 v60, v60, v60
	v_fmac_f32_e32 v62, v61, v61
	v_fmac_f32_e32 v60, v55, v55
	v_fmamk_f32 v61, v54, 0xba800000, v47
	v_fmamk_f32 v63, v54, 0xba800000, v49
	v_add_f32_e32 v55, v62, v60
	v_fmamk_f32 v60, v54, 0xba800000, v46
	v_fmamk_f32 v62, v54, 0xba800000, v48
	v_mul_f32_e32 v63, v63, v63
	v_mul_f32_e32 v61, v61, v61
	v_fmac_f32_e32 v63, v62, v62
	v_fmac_f32_e32 v61, v60, v60
	v_add_f32_e32 v60, v63, v61
	v_fmamk_f32 v61, v54, 0xba800000, v57
	v_fmamk_f32 v63, v54, 0xba800000, v59
	v_add_f32_e32 v55, v55, v60
	v_fmamk_f32 v60, v54, 0xba800000, v56
	v_fmamk_f32 v62, v54, 0xba800000, v58
	v_mul_f32_e32 v63, v63, v63
	v_mul_f32_e32 v61, v61, v61
	v_fmac_f32_e32 v63, v62, v62
	v_fmac_f32_e32 v61, v60, v60
	v_add_f32_e32 v60, v63, v61
	v_fmamk_f32 v61, v54, 0xba800000, v3
	v_fmamk_f32 v63, v54, 0xba800000, v5
	v_add_f32_e32 v55, v60, v55
	v_fmamk_f32 v60, v54, 0xba800000, v2
	v_fmamk_f32 v62, v54, 0xba800000, v4
	v_mul_f32_e32 v63, v63, v63
	v_mul_f32_e32 v61, v61, v61
	v_fmac_f32_e32 v63, v62, v62
	v_fmac_f32_e32 v61, v60, v60
	v_add_f32_e32 v60, v63, v61
	v_add_f32_e32 v55, v60, v55
	ds_bpermute_b32 v60, v1, v55
	s_waitcnt lgkmcnt(0)
	v_add_f32_e32 v55, v55, v60
	ds_bpermute_b32 v60, v92, v55
	s_waitcnt lgkmcnt(0)
	v_add_f32_e32 v55, v55, v60
	ds_bpermute_b32 v60, v93, v55
	s_waitcnt lgkmcnt(0)
	v_add_f32_e32 v55, v55, v60
	ds_bpermute_b32 v60, v94, v55
	s_waitcnt lgkmcnt(0)
	v_add_f32_e32 v55, v55, v60
	ds_bpermute_b32 v60, v95, v55
	s_waitcnt lgkmcnt(0)
	v_add_f32_e32 v55, v55, v60
	ds_bpermute_b32 v60, v96, v55
	s_and_saveexec_b64 s[12:13], s[40:41]
	s_cbranch_execz .LBB0_1422
	v_mul_f32_e32 v54, 0x3a800000, v54
	s_waitcnt lgkmcnt(0)
	v_add_f32_e32 v55, v55, v60
	v_mov_b32_e32 v60, s22
	ds_write_b64 v60, v[54:55]
; #define GAS __attribute__((address_space(1)))
; __device__ __forceinline__ unsigned pk2(float lo, float hi) { unsigned r; asm("v_cvt_pk_bf16_f32 %0, %1, %2" : "=v"(r) : "v"(lo), "v"(hi)); return r; }
; __device__ __forceinline__ void ln_phase(Frame& F, CArgs a, int l, int which) {
;     ...
;         __syncthreads();
;         const f32x2v s0 = XS[p], s1 = XS[p + 4];
;         const float mean = 0.5f * (s0.x + s1.x), d0 = s0.x - mean, d1 = s1.x - mean;
;         const float rstd = 1.0f / sqrtf(((s0.y + s1.y) + 1024.0f * (d0 * d0 + d1 * d1)) * (1.0f / D) + LN_EPS);
;         if (!valid) continue;
;         const GAS float* sh = mod + (size_t)3 * 12288; const GAS float* sc = sh + D;
;         GAS f16_t* xo = X + (size_t)row * D;
;         GAS u32x2* xm = (GAS u32x2*)(XM + (size_t)row * D);
; #pragma unroll
;         for (int j = 0; j < 4; ++j) { const int i4 = lane + 64 * (j + 4 * half); const f32x4 y = (v[j] - mean) * rstd * ((const GAS f32x4*)g)[i4] + ((const GAS f32x4*)bb)[i4];
;             stx4(xo + i4 * 4, y);
;             const f32x4 r = y * (((const GAS f32x4*)sc)[i4] + 1.0f) + ((const GAS f32x4*)sh)[i4]; u32x2 w; w.x = pk2(r[0], r[1]); w.y = pk2(r[2], r[3]); xm[i4] = w; }
.LBB0_1422:
	s_or_b64 exec, exec, s[12:13]
	s_andn2_b64 vcc, exec, s[10:11]
	s_waitcnt lgkmcnt(0)
	s_barrier
	s_cbranch_vccnz .LBB0_1419
	v_mov_b32_e32 v54, s19
	ds_read2_b64 v[60:63], v54 offset1:4
	s_mov_b32 s10, 0xf800000
	s_lshl_b64 s[8:9], s[8:9], 11
	s_waitcnt lgkmcnt(0)
	v_add_f32_e32 v55, v60, v62
	v_fma_f32 v54, -0.5, v55, v60
	v_mul_f32_e32 v65, v54, v54
	v_fma_f32 v54, -0.5, v55, v62
	v_mul_f32_e32 v67, v54, v54
	v_mov_b32_e32 v64, v61
	v_mov_b32_e32 v66, v63
	v_pk_add_f32 v[60:61], v[64:65], v[66:67]
	v_fma_f32 v51, -0.5, v55, v51
	v_fmac_f32_e32 v60, 0x44800000, v61
	v_fmamk_f32 v54, v60, 0x3a000000, v230
	v_cmp_gt_f32_e32 vcc, s10, v54
	v_mul_f32_e32 v60, 0x4f800000, v54
	v_fmac_f32_e32 v50, -0.5, v55
	v_cndmask_b32_e32 v54, v54, v60, vcc
	v_sqrt_f32_e32 v60, v54
	v_fma_f32 v53, -0.5, v55, v53
	v_fmac_f32_e32 v52, -0.5, v55
	v_fma_f32 v47, -0.5, v55, v47
	v_add_u32_e32 v61, -1, v60
	v_fma_f32 v62, -v61, v60, v54
	v_cmp_ge_f32_e64 s[42:43], 0, v62
	v_add_u32_e32 v62, 1, v60
	v_fmac_f32_e32 v46, -0.5, v55
	v_cndmask_b32_e64 v61, v60, v61, s[42:43]
	v_fma_f32 v60, -v62, v60, v54
	v_cmp_lt_f32_e64 s[42:43], 0, v60
	v_fma_f32 v49, -0.5, v55, v49
	v_fmac_f32_e32 v48, -0.5, v55
	v_cndmask_b32_e64 v60, v61, v62, s[42:43]
	v_mul_f32_e32 v61, 0x37800000, v60
	v_cndmask_b32_e32 v60, v60, v61, vcc
	v_cmp_class_f32_e32 vcc, v54, v229
	v_fma_f32 v57, -0.5, v55, v57
	v_fmac_f32_e32 v56, -0.5, v55
	v_cndmask_b32_e32 v54, v60, v54, vcc
	v_div_scale_f32 v60, s[10:11], v54, v54, 1.0
	v_rcp_f32_e32 v61, v60
	s_lshl_b64 s[10:11], s[8:9], 1
	s_add_u32 s8, s4, s10
	s_addc_u32 s9, s5, s11
	v_fma_f32 v62, -v60, v61, 1.0
	v_fmac_f32_e32 v61, v62, v61
	v_div_scale_f32 v62, vcc, 1.0, v54, 1.0
	v_mul_f32_e32 v63, v62, v61
	v_fma_f32 v64, -v60, v63, v62
	v_fmac_f32_e32 v63, v64, v61
	v_fma_f32 v60, -v60, v63, v62
	v_div_fmas_f32 v60, v60, v61, v63
	v_div_fixup_f32 v54, v60, v54, 1.0
	v_pk_mul_f32 v[64:65], v[52:53], v[54:55] op_sel_hi:[1,0]
	v_pk_mul_f32 v[66:67], v[50:51], v[54:55] op_sel_hi:[1,0]
	v_fma_f32 v59, -0.5, v55, v59
	v_fmac_f32_e32 v58, -0.5, v55
	v_fma_f32 v3, -0.5, v55, v3
	v_fmac_f32_e32 v2, -0.5, v55
	v_fma_f32 v5, -0.5, v55, v5
	v_fmac_f32_e32 v4, -0.5, v55
	s_waitcnt vmcnt(0)
	v_pk_fma_f32 v[62:63], v[102:103], v[66:67], v[106:107]
	v_pk_fma_f32 v[60:61], v[100:101], v[64:65], v[104:105]
	v_med3_f32 v53, v62, s84, v245
	v_med3_f32 v52, v60, s84, v245
	v_med3_f32 v64, v61, s84, v245
	v_med3_f32 v65, v63, s84, v245
	v_lshl_add_u64 v[50:51], v[6:7], 1, s[8:9]
	v_cvt_pk_f16_f32 v53, v53, v65
	v_cvt_pk_f16_f32 v52, v52, v64
	global_store_dwordx2 v[50:51], v[52:53], off
	v_pk_add_f32 v[64:65], v[110:111], 1.0 op_sel_hi:[1,0]
	v_pk_add_f32 v[66:67], v[108:109], 1.0 op_sel_hi:[1,0]
	v_pk_fma_f32 v[50:51], v[66:67], v[60:61], v[112:113]
	s_nop 0
	v_cvt_pk_bf16_f32 v60, v50, v51
	v_lshl_add_u64 v[50:51], v[44:45], 0, s[10:11]
	v_pk_fma_f32 v[52:53], v[64:65], v[62:63], v[114:115]
	v_pk_mul_f32 v[64:65], v[46:47], v[54:55] op_sel_hi:[1,0]
	v_cvt_pk_bf16_f32 v61, v52, v53
	global_store_dwordx2 v[50:51], v[60:61], off
	v_pk_mul_f32 v[52:53], v[48:49], v[54:55] op_sel_hi:[1,0]
	v_pk_fma_f32 v[62:63], v[118:119], v[64:65], v[122:123]
	v_pk_fma_f32 v[52:53], v[116:117], v[52:53], v[120:121]
	v_med3_f32 v60, v62, s84, v245
	v_med3_f32 v48, v52, s84, v245
	v_med3_f32 v49, v53, s84, v245
	v_med3_f32 v61, v63, s84, v245
	v_lshl_add_u64 v[46:47], v[10:11], 1, s[8:9]
	v_cvt_pk_f16_f32 v48, v48, v49
	v_cvt_pk_f16_f32 v49, v60, v61
	global_store_dwordx2 v[46:47], v[48:49], off
	v_pk_add_f32 v[60:61], v[126:127], 1.0 op_sel_hi:[1,0]
	v_pk_add_f32 v[64:65], v[124:125], 1.0 op_sel_hi:[1,0]
	v_pk_fma_f32 v[46:47], v[64:65], v[52:53], v[128:129]
	v_pk_fma_f32 v[48:49], v[60:61], v[62:63], v[130:131]
	v_cvt_pk_bf16_f32 v46, v46, v47
	v_pk_mul_f32 v[52:53], v[58:59], v[54:55] op_sel_hi:[1,0]
	v_cvt_pk_bf16_f32 v47, v48, v49
	global_store_dwordx2 v[50:51], v[46:47], off offset:512
	v_pk_mul_f32 v[60:61], v[56:57], v[54:55] op_sel_hi:[1,0]
	v_pk_fma_f32 v[58:59], v[60:61], v[134:135], v[138:139]
	v_pk_fma_f32 v[52:53], v[52:53], v[132:133], v[136:137]
	v_med3_f32 v56, v58, s84, v245
	v_med3_f32 v48, v52, s84, v245
	v_med3_f32 v49, v53, s84, v245
	v_med3_f32 v57, v59, s84, v245
	v_lshl_add_u64 v[46:47], v[14:15], 1, s[8:9]
	v_cvt_pk_f16_f32 v48, v48, v49
	v_cvt_pk_f16_f32 v49, v56, v57
	global_store_dwordx2 v[46:47], v[48:49], off
	v_pk_add_f32 v[56:57], v[142:143], 1.0 op_sel_hi:[1,0]
	v_pk_add_f32 v[60:61], v[140:141], 1.0 op_sel_hi:[1,0]
	v_pk_fma_f32 v[46:47], v[52:53], v[60:61], v[144:145]
	v_pk_fma_f32 v[48:49], v[58:59], v[56:57], v[146:147]
	v_cvt_pk_bf16_f32 v46, v46, v47
	v_pk_mul_f32 v[52:53], v[4:5], v[54:55] op_sel_hi:[1,0]
	v_cvt_pk_bf16_f32 v47, v48, v49
	global_store_dwordx2 v[50:51], v[46:47], off offset:1024
	v_pk_mul_f32 v[54:55], v[2:3], v[54:55] op_sel_hi:[1,0]
	v_pk_fma_f32 v[48:49], v[54:55], v[150:151], v[154:155]
	v_pk_fma_f32 v[46:47], v[52:53], v[148:149], v[152:153]
	v_med3_f32 v52, v48, s84, v245
	v_med3_f32 v4, v46, s84, v245
	v_med3_f32 v5, v47, s84, v245
	v_med3_f32 v53, v49, s84, v245
	v_lshl_add_u64 v[2:3], v[18:19], 1, s[8:9]
	v_cvt_pk_f16_f32 v4, v4, v5
	v_cvt_pk_f16_f32 v5, v52, v53
	global_store_dwordx2 v[2:3], v[4:5], off
	v_pk_add_f32 v[52:53], v[158:159], 1.0 op_sel_hi:[1,0]
	v_pk_add_f32 v[54:55], v[156:157], 1.0 op_sel_hi:[1,0]
	v_pk_fma_f32 v[2:3], v[46:47], v[54:55], v[160:161]
	v_pk_fma_f32 v[4:5], v[48:49], v[52:53], v[162:163]
	v_cvt_pk_bf16_f32 v2, v2, v3
	s_nop 0
	v_cvt_pk_bf16_f32 v3, v4, v5
	global_store_dwordx2 v[50:51], v[2:3], off offset:1536
	s_branch .LBB0_1419

; #define GAS __attribute__((address_space(1)))
; __device__ __forceinline__ f32x4 ldx4(const GAS f16_t* p) { const f16x4 h = *(const GAS f16x4*)p; return __builtin_convertvector(h, f32x4); }
; __device__ __forceinline__ void ln_phase(Frame& F, CArgs a, int l, int which) {
;     ...
;     for (int base = 0; base < 1024; base += 4 * F.G) {
;         const int rr = base + p * F.G + F.blk; const bool valid = rr < 1024; const int row = 8192 + (valid ? rr : 0);
;         const GAS f32x4* sr = (const GAS f32x4*)(S + (size_t)row * D);
;         f32x4 v[4]; float s = 0.f;
; #pragma unroll
;         for (int j = 0; j < 4; ++j) {
;             const int i4 = lane + 64 * (j + 4 * half);
;             f32x4 t8[8]; t8[0] = sr[i4];
; #pragma unroll
;             for (int q = 0; q < 7; ++q) t8[q + 1] = ldx4(PBp + ((size_t)q * 1024 + (row - 8192)) * D + i4 * 4);
;             v[j] = ((t8[0] + t8[1]) + (t8[2] + t8[3])) + ((t8[4] + t8[5]) + (t8[6] + t8[7]));
;             s += (v[j][0] + v[j][1]) + (v[j][2] + v[j][3]); }
.LBB0_1922:
	s_add_i32 s12, s23, s18
	s_cmpk_lt_i32 s12, 0x400
	s_cselect_b64 s[10:11], -1, 0
	s_and_b64 s[8:9], s[10:11], exec
	s_cselect_b32 s12, s12, 0
	s_add_i32 s8, s12, 0x2000
	s_ashr_i32 s9, s8, 31
	s_ashr_i32 s13, s12, 31
	s_lshl_b64 s[12:13], s[12:13], 12
	s_lshl_b64 s[24:25], s[8:9], 13
	v_lshl_add_u64 v[62:63], v[42:43], 0, s[24:25]
	s_load_dwordx2 s[100:101], s[0:1], 0x130
	s_waitcnt lgkmcnt(0)
	s_add_u32 s100, s100, 0x46000000
	s_addc_u32 s101, s101, 0
	s_add_u32 s100, s100, s12
	s_addc_u32 s101, s101, s13
	v_lshlrev_b32_e32 v172, 1, v6
	v_lshlrev_b32_e32 v173, 1, v10
	v_lshlrev_b32_e32 v174, 1, v14
	v_lshlrev_b32_e32 v175, 1, v18
	global_load_dwordx4 v[104:107], v[62:63], off
	global_load_dwordx4 v[122:125], v[62:63], off offset:1024
	global_load_dwordx4 v[140:143], v[62:63], off offset:2048
	global_load_dwordx4 v[156:159], v[62:63], off offset:3072
	global_load_dwordx2 v[100:101], v172, s[100:101]
	global_load_dwordx2 v[118:119], v173, s[100:101]
	global_load_dwordx2 v[138:139], v174, s[100:101]
	global_load_dwordx2 v[148:149], v175, s[100:101]
	s_add_u32 s100, s100, 0x400000
	s_addc_u32 s101, s101, 0
	global_load_dwordx2 v[102:103], v172, s[100:101]
	global_load_dwordx2 v[120:121], v173, s[100:101]
	global_load_dwordx2 v[136:137], v174, s[100:101]
	global_load_dwordx2 v[160:161], v175, s[100:101]
	s_add_u32 s100, s100, 0x400000
	s_addc_u32 s101, s101, 0
	global_load_dwordx2 v[108:109], v172, s[100:101]
	global_load_dwordx2 v[126:127], v173, s[100:101]
	global_load_dwordx2 v[144:145], v174, s[100:101]
	global_load_dwordx2 v[162:163], v175, s[100:101]
	s_add_u32 s100, s100, 0x400000
	s_addc_u32 s101, s101, 0
	global_load_dwordx2 v[110:111], v172, s[100:101]
	global_load_dwordx2 v[128:129], v173, s[100:101]
	global_load_dwordx2 v[146:147], v174, s[100:101]
	global_load_dwordx2 v[164:165], v175, s[100:101]
	s_add_u32 s100, s100, 0x400000
	s_addc_u32 s101, s101, 0
	global_load_dwordx2 v[112:113], v172, s[100:101]
	global_load_dwordx2 v[130:131], v173, s[100:101]
	global_load_dwordx2 v[150:151], v174, s[100:101]
	global_load_dwordx2 v[166:167], v175, s[100:101]
	s_add_u32 s100, s100, 0x400000
	s_addc_u32 s101, s101, 0
	global_load_dwordx2 v[114:115], v172, s[100:101]
	global_load_dwordx2 v[132:133], v173, s[100:101]
	global_load_dwordx2 v[152:153], v174, s[100:101]
	global_load_dwordx2 v[168:169], v175, s[100:101]
	s_add_u32 s100, s100, 0x400000
	s_addc_u32 s101, s101, 0
	global_load_dwordx2 v[116:117], v172, s[100:101]
	global_load_dwordx2 v[134:135], v173, s[100:101]
	global_load_dwordx2 v[154:155], v174, s[100:101]
	global_load_dwordx2 v[170:171], v175, s[100:101]
	s_waitcnt vmcnt(0)
	v_lshl_add_u64 v[46:47], v[8:9], 0, s[12:13]
	s_mov_b32 s24, 0x400000
	v_add_co_u32_e32 v52, vcc, s24, v46
	s_nop 0
	v_addc_co_u32_e32 v53, vcc, 0, v47, vcc
	s_mov_b32 s25, 0x800000
	s_mov_b32 s26, 0xc00000
	s_mov_b32 s27, 0x1000000
	s_mov_b32 s34, 0x1400000
	s_mov_b32 s35, 0x1800000
	v_lshl_add_u64 v[90:91], v[20:21], 0, s[12:13]
	v_cvt_f32_f16_e32 v50, v100
	v_cvt_f32_f16_sdwa v51, v100 dst_sel:DWORD dst_unused:UNUSED_PAD src0_sel:WORD_1
	v_cvt_f32_f16_e32 v48, v101
	v_cvt_f32_f16_e32 v56, v102
	v_cvt_f32_f16_sdwa v57, v102 dst_sel:DWORD dst_unused:UNUSED_PAD src0_sel:WORD_1
	v_add_co_u32_e32 v52, vcc, s25, v46
	v_cvt_f32_f16_e32 v54, v103
	v_cvt_f32_f16_sdwa v55, v103 dst_sel:DWORD dst_unused:UNUSED_PAD src0_sel:WORD_1
	v_addc_co_u32_e32 v53, vcc, 0, v47, vcc
	v_cvt_f32_f16_sdwa v49, v101 dst_sel:DWORD dst_unused:UNUSED_PAD src0_sel:WORD_1
	v_pk_add_f32 v[2:3], v[104:105], v[50:51]
	v_pk_add_f32 v[4:5], v[106:107], v[48:49]
	v_cvt_f32_f16_e32 v60, v108
	v_cvt_f32_f16_sdwa v61, v108 dst_sel:DWORD dst_unused:UNUSED_PAD src0_sel:WORD_1
	v_add_co_u32_e32 v52, vcc, s26, v46
	v_cvt_f32_f16_e32 v58, v109
	v_cvt_f32_f16_sdwa v59, v109 dst_sel:DWORD dst_unused:UNUSED_PAD src0_sel:WORD_1
	v_addc_co_u32_e32 v53, vcc, 0, v47, vcc
	v_pk_add_f32 v[48:49], v[54:55], v[58:59]
	v_cvt_f32_f16_e32 v66, v110
	v_cvt_f32_f16_sdwa v67, v110 dst_sel:DWORD dst_unused:UNUSED_PAD src0_sel:WORD_1
	v_add_co_u32_e32 v52, vcc, s27, v46
	v_cvt_f32_f16_e32 v64, v111
	v_cvt_f32_f16_sdwa v65, v111 dst_sel:DWORD dst_unused:UNUSED_PAD src0_sel:WORD_1
	v_addc_co_u32_e32 v53, vcc, 0, v47, vcc
	v_pk_add_f32 v[4:5], v[4:5], v[48:49]
	v_cvt_f32_f16_e32 v70, v112
	v_cvt_f32_f16_sdwa v71, v112 dst_sel:DWORD dst_unused:UNUSED_PAD src0_sel:WORD_1
	v_add_co_u32_e32 v52, vcc, s34, v46
	v_cvt_f32_f16_e32 v68, v113
	v_cvt_f32_f16_sdwa v69, v113 dst_sel:DWORD dst_unused:UNUSED_PAD src0_sel:WORD_1
	v_addc_co_u32_e32 v53, vcc, 0, v47, vcc
	v_add_co_u32_e32 v46, vcc, s35, v46
	s_nop 0
	v_addc_co_u32_e32 v47, vcc, 0, v47, vcc
	v_pk_add_f32 v[48:49], v[64:65], v[68:69]
	v_cvt_f32_f16_e32 v74, v114
	v_cvt_f32_f16_sdwa v75, v114 dst_sel:DWORD dst_unused:UNUSED_PAD src0_sel:WORD_1
	v_cvt_f32_f16_e32 v72, v115
	v_cvt_f32_f16_e32 v76, v116
	v_cvt_f32_f16_sdwa v77, v116 dst_sel:DWORD dst_unused:UNUSED_PAD src0_sel:WORD_1
	v_cvt_f32_f16_sdwa v73, v115 dst_sel:DWORD dst_unused:UNUSED_PAD src0_sel:WORD_1
	v_cvt_f32_f16_e32 v52, v117
	v_cvt_f32_f16_sdwa v53, v117 dst_sel:DWORD dst_unused:UNUSED_PAD src0_sel:WORD_1
	v_pk_add_f32 v[46:47], v[56:57], v[60:61]
	v_pk_add_f32 v[50:51], v[74:75], v[76:77]
	v_pk_add_f32 v[2:3], v[2:3], v[46:47]
	v_pk_add_f32 v[46:47], v[66:67], v[70:71]
	v_pk_add_f32 v[52:53], v[72:73], v[52:53]
	v_pk_add_f32 v[46:47], v[46:47], v[50:51]
	v_pk_add_f32 v[48:49], v[48:49], v[52:53]
	v_pk_add_f32 v[52:53], v[2:3], v[46:47]
	v_lshl_add_u64 v[46:47], v[12:13], 0, s[12:13]
	v_add_co_u32_e32 v58, vcc, s24, v46
	v_pk_add_f32 v[50:51], v[4:5], v[48:49]
	s_nop 0
	v_addc_co_u32_e32 v59, vcc, 0, v47, vcc
; __device__ __forceinline__ f32x4 ldx4(const GAS f16_t* p) { const f16x4 h = *(const GAS f16x4*)p; return __builtin_convertvector(h, f32x4); }
; __device__ __forceinline__ void ln_phase(Frame& F, CArgs a, int l, int which) {
;     ...
;         for (int j = 0; j < 4; ++j) {
;             const int i4 = lane + 64 * (j + 4 * half);
;             f32x4 t8[8]; t8[0] = sr[i4];
; #pragma unroll
;             for (int q = 0; q < 7; ++q) t8[q + 1] = ldx4(PBp + ((size_t)q * 1024 + (row - 8192)) * D + i4 * 4);
;             v[j] = ((t8[0] + t8[1]) + (t8[2] + t8[3])) + ((t8[4] + t8[5]) + (t8[6] + t8[7]));
;             s += (v[j][0] + v[j][1]) + (v[j][2] + v[j][3]); }
	v_pk_mov_b32 v[2:3], v[52:53], v[50:51] op_sel:[1,0]
	v_mov_b32_e32 v4, v52
	v_mov_b32_e32 v5, v51
	v_pk_add_f32 v[2:3], v[2:3], v[4:5]
	v_cvt_f32_f16_e32 v56, v118
	v_add_f32_e32 v2, v2, v3
	v_cvt_f32_f16_e32 v64, v120
	v_cvt_f32_f16_sdwa v65, v120 dst_sel:DWORD dst_unused:UNUSED_PAD src0_sel:WORD_1
	v_add_co_u32_e32 v58, vcc, s25, v46
	v_cvt_f32_f16_e32 v60, v121
	v_cvt_f32_f16_sdwa v61, v121 dst_sel:DWORD dst_unused:UNUSED_PAD src0_sel:WORD_1
	v_addc_co_u32_e32 v59, vcc, 0, v47, vcc
	v_add_f32_e32 v54, 0, v2
	v_cvt_f32_f16_sdwa v57, v118 dst_sel:DWORD dst_unused:UNUSED_PAD src0_sel:WORD_1
	v_cvt_f32_f16_e32 v48, v119
	v_cvt_f32_f16_sdwa v49, v119 dst_sel:DWORD dst_unused:UNUSED_PAD src0_sel:WORD_1
	v_pk_add_f32 v[2:3], v[122:123], v[56:57]
	v_pk_add_f32 v[4:5], v[124:125], v[48:49]
	v_cvt_f32_f16_e32 v68, v126
	v_cvt_f32_f16_sdwa v69, v126 dst_sel:DWORD dst_unused:UNUSED_PAD src0_sel:WORD_1
	v_add_co_u32_e32 v58, vcc, s26, v46
	v_cvt_f32_f16_e32 v66, v127
	v_cvt_f32_f16_sdwa v67, v127 dst_sel:DWORD dst_unused:UNUSED_PAD src0_sel:WORD_1
	v_addc_co_u32_e32 v59, vcc, 0, v47, vcc
	v_pk_add_f32 v[48:49], v[60:61], v[66:67]
	v_cvt_f32_f16_e32 v72, v128
	v_cvt_f32_f16_sdwa v73, v128 dst_sel:DWORD dst_unused:UNUSED_PAD src0_sel:WORD_1
	v_add_co_u32_e32 v58, vcc, s27, v46
	v_cvt_f32_f16_e32 v70, v129
	v_cvt_f32_f16_sdwa v71, v129 dst_sel:DWORD dst_unused:UNUSED_PAD src0_sel:WORD_1
	v_addc_co_u32_e32 v59, vcc, 0, v47, vcc
	v_pk_add_f32 v[4:5], v[4:5], v[48:49]
	v_cvt_f32_f16_e32 v76, v130
	v_cvt_f32_f16_sdwa v77, v130 dst_sel:DWORD dst_unused:UNUSED_PAD src0_sel:WORD_1
	v_add_co_u32_e32 v58, vcc, s34, v46
	v_cvt_f32_f16_e32 v74, v131
	v_cvt_f32_f16_sdwa v75, v131 dst_sel:DWORD dst_unused:UNUSED_PAD src0_sel:WORD_1
	v_addc_co_u32_e32 v59, vcc, 0, v47, vcc
	v_add_co_u32_e32 v46, vcc, s35, v46
	s_nop 0
	v_addc_co_u32_e32 v47, vcc, 0, v47, vcc
	v_pk_add_f32 v[48:49], v[70:71], v[74:75]
	v_cvt_f32_f16_e32 v80, v132
	v_cvt_f32_f16_sdwa v81, v132 dst_sel:DWORD dst_unused:UNUSED_PAD src0_sel:WORD_1
	v_cvt_f32_f16_e32 v78, v133
	v_cvt_f32_f16_e32 v82, v134
	v_cvt_f32_f16_sdwa v83, v134 dst_sel:DWORD dst_unused:UNUSED_PAD src0_sel:WORD_1
	v_cvt_f32_f16_sdwa v79, v133 dst_sel:DWORD dst_unused:UNUSED_PAD src0_sel:WORD_1
	v_cvt_f32_f16_e32 v58, v135
	v_cvt_f32_f16_sdwa v59, v135 dst_sel:DWORD dst_unused:UNUSED_PAD src0_sel:WORD_1
	v_pk_add_f32 v[46:47], v[64:65], v[68:69]
	v_pk_add_f32 v[56:57], v[80:81], v[82:83]
	v_pk_add_f32 v[2:3], v[2:3], v[46:47]
	v_pk_add_f32 v[46:47], v[72:73], v[76:77]
	v_pk_add_f32 v[58:59], v[78:79], v[58:59]
	v_pk_add_f32 v[46:47], v[46:47], v[56:57]
	v_lshl_add_u64 v[56:57], v[16:17], 0, s[12:13]
	v_add_co_u32_e32 v66, vcc, s24, v56
	v_pk_add_f32 v[58:59], v[48:49], v[58:59]
	s_nop 0
	v_addc_co_u32_e32 v67, vcc, 0, v57, vcc
	v_pk_add_f32 v[48:49], v[2:3], v[46:47]
	v_pk_add_f32 v[46:47], v[4:5], v[58:59]
	v_mov_b32_e32 v4, v48
	v_pk_mov_b32 v[2:3], v[48:49], v[46:47] op_sel:[1,0]
	v_mov_b32_e32 v5, v47
	v_pk_add_f32 v[2:3], v[2:3], v[4:5]
	v_pk_add_f32 v[60:61], v[2:3], v[2:3] op_sel:[0,1] op_sel_hi:[1,0]
	v_cvt_f32_f16_e32 v70, v136
	v_cvt_f32_f16_sdwa v71, v136 dst_sel:DWORD dst_unused:UNUSED_PAD src0_sel:WORD_1
	v_add_co_u32_e32 v66, vcc, s25, v56
	v_cvt_f32_f16_e32 v68, v137
	v_cvt_f32_f16_sdwa v69, v137 dst_sel:DWORD dst_unused:UNUSED_PAD src0_sel:WORD_1
	v_addc_co_u32_e32 v67, vcc, 0, v57, vcc
	v_cvt_f32_f16_e32 v64, v138
	v_cvt_f32_f16_sdwa v65, v138 dst_sel:DWORD dst_unused:UNUSED_PAD src0_sel:WORD_1
	v_cvt_f32_f16_e32 v58, v139
	v_cvt_f32_f16_sdwa v59, v139 dst_sel:DWORD dst_unused:UNUSED_PAD src0_sel:WORD_1
	v_pk_add_f32 v[2:3], v[140:141], v[64:65]
	v_pk_add_f32 v[4:5], v[142:143], v[58:59]
	v_cvt_f32_f16_e32 v74, v144
	v_cvt_f32_f16_sdwa v75, v144 dst_sel:DWORD dst_unused:UNUSED_PAD src0_sel:WORD_1
	v_add_co_u32_e32 v66, vcc, s26, v56
	v_cvt_f32_f16_e32 v72, v145
	v_cvt_f32_f16_sdwa v73, v145 dst_sel:DWORD dst_unused:UNUSED_PAD src0_sel:WORD_1
	v_addc_co_u32_e32 v67, vcc, 0, v57, vcc
	v_pk_add_f32 v[58:59], v[68:69], v[72:73]
	v_pk_add_f32 v[4:5], v[4:5], v[58:59]
	v_cvt_f32_f16_e32 v78, v146
	v_cvt_f32_f16_sdwa v79, v146 dst_sel:DWORD dst_unused:UNUSED_PAD src0_sel:WORD_1
	v_add_co_u32_e32 v66, vcc, s27, v56
	v_cvt_f32_f16_e32 v76, v147
	v_cvt_f32_f16_sdwa v77, v147 dst_sel:DWORD dst_unused:UNUSED_PAD src0_sel:WORD_1
	v_addc_co_u32_e32 v67, vcc, 0, v57, vcc
	v_cvt_f32_f16_e32 v82, v150
	v_cvt_f32_f16_sdwa v83, v150 dst_sel:DWORD dst_unused:UNUSED_PAD src0_sel:WORD_1
	v_add_co_u32_e32 v66, vcc, s34, v56
	v_cvt_f32_f16_e32 v80, v151
	v_cvt_f32_f16_sdwa v81, v151 dst_sel:DWORD dst_unused:UNUSED_PAD src0_sel:WORD_1
	v_addc_co_u32_e32 v67, vcc, 0, v57, vcc
	v_add_co_u32_e32 v56, vcc, s35, v56
	s_nop 0
	v_addc_co_u32_e32 v57, vcc, 0, v57, vcc
	v_pk_add_f32 v[58:59], v[76:77], v[80:81]
	v_cvt_f32_f16_e32 v84, v153
	v_cvt_f32_f16_sdwa v85, v153 dst_sel:DWORD dst_unused:UNUSED_PAD src0_sel:WORD_1
	v_cvt_f32_f16_e32 v86, v152
	v_cvt_f32_f16_sdwa v87, v152 dst_sel:DWORD dst_unused:UNUSED_PAD src0_sel:WORD_1
	v_cvt_f32_f16_e32 v66, v155
	v_cvt_f32_f16_sdwa v67, v155 dst_sel:DWORD dst_unused:UNUSED_PAD src0_sel:WORD_1
	v_cvt_f32_f16_e32 v88, v154
	v_cvt_f32_f16_sdwa v89, v154 dst_sel:DWORD dst_unused:UNUSED_PAD src0_sel:WORD_1
	v_pk_add_f32 v[56:57], v[70:71], v[74:75]
	v_add_co_u32_e32 v70, vcc, s24, v90
	v_pk_add_f32 v[2:3], v[2:3], v[56:57]
	s_nop 0
	v_addc_co_u32_e32 v71, vcc, 0, v91, vcc
	v_add_co_u32_e32 v74, vcc, s25, v90
	v_pk_add_f32 v[56:57], v[78:79], v[82:83]
	s_nop 0
	v_addc_co_u32_e32 v75, vcc, 0, v91, vcc
	v_add_co_u32_e32 v78, vcc, s26, v90
	v_pk_add_f32 v[64:65], v[86:87], v[88:89]
	s_nop 0
	v_addc_co_u32_e32 v79, vcc, 0, v91, vcc
	v_add_co_u32_e32 v82, vcc, s27, v90
	v_pk_add_f32 v[66:67], v[84:85], v[66:67]
	s_nop 0
	v_addc_co_u32_e32 v83, vcc, 0, v91, vcc
	v_add_co_u32_e32 v86, vcc, s34, v90
	v_pk_add_f32 v[66:67], v[58:59], v[66:67]
	s_nop 0
	v_addc_co_u32_e32 v87, vcc, 0, v91, vcc
	v_pk_add_f32 v[56:57], v[56:57], v[64:65]
	v_add_co_u32_e32 v90, vcc, s35, v90
	v_pk_add_f32 v[58:59], v[2:3], v[56:57]
	v_pk_add_f32 v[56:57], v[4:5], v[66:67]
	v_addc_co_u32_e32 v91, vcc, 0, v91, vcc
	v_cvt_f32_f16_e32 v62, v148
	v_cvt_f32_f16_sdwa v63, v148 dst_sel:DWORD dst_unused:UNUSED_PAD src0_sel:WORD_1
	v_cvt_f32_f16_e32 v68, v149
	v_cvt_f32_f16_sdwa v69, v149 dst_sel:DWORD dst_unused:UNUSED_PAD src0_sel:WORD_1
	v_add_f32_e32 v64, v58, v59
	v_add_f32_e32 v66, v56, v57
	s_barrier
; #define GAS __attribute__((address_space(1)))
; __device__ __forceinline__ unsigned pk2(float lo, float hi) { unsigned r; asm("v_cvt_pk_bf16_f32 %0, %1, %2" : "=v"(r) : "v"(lo), "v"(hi)); return r; }
; __device__ __forceinline__ void ln_phase(Frame& F, CArgs a, int l, int which) {
;     ...
;             v[j] = ((t8[0] + t8[1]) + (t8[2] + t8[3])) + ((t8[4] + t8[5]) + (t8[6] + t8[7]));
;             s += (v[j][0] + v[j][1]) + (v[j][2] + v[j][3]); }
;         const float mh = wave_sum(s) * (1.0f / 1024.0f); float q = 0.f;
; #pragma unroll
;         for (int j = 0; j < 4; ++j) { const f32x4 d = v[j] - mh; q += (d[0] * d[0] + d[1] * d[1]) + (d[2] * d[2] + d[3] * d[3]); }
;         q = wave_sum(q);
;         __syncthreads();
;         if (lane == 0) XS[F.wave] = (f32x2v){mh, q};
;     ...
;         for (int j = 0; j < 4; ++j) { const int i4 = lane + 64 * (j + 4 * half); const f32x4 y = (v[j] - mean) * rstd * ((const GAS f32x4*)g)[i4] + ((const GAS f32x4*)bb)[i4];
;             stx4(xo + i4 * 4, y);
;             const f32x4 r = y * (((const GAS f32x4*)sc)[i4] + 1.0f) + ((const GAS f32x4*)sh)[i4]; u32x2 w; w.x = pk2(r[0], r[1]); w.y = pk2(r[2], r[3]); xm[i4] = w; }
	v_pk_add_f32 v[4:5], v[158:159], v[68:69]
	v_cvt_f32_f16_e32 v70, v160
	v_cvt_f32_f16_sdwa v71, v160 dst_sel:DWORD dst_unused:UNUSED_PAD src0_sel:WORD_1
	v_cvt_f32_f16_e32 v72, v161
	v_cvt_f32_f16_sdwa v73, v161 dst_sel:DWORD dst_unused:UNUSED_PAD src0_sel:WORD_1
	v_cvt_f32_f16_e32 v74, v162
	v_cvt_f32_f16_sdwa v75, v162 dst_sel:DWORD dst_unused:UNUSED_PAD src0_sel:WORD_1
	v_cvt_f32_f16_e32 v76, v163
	v_cvt_f32_f16_sdwa v77, v163 dst_sel:DWORD dst_unused:UNUSED_PAD src0_sel:WORD_1
	v_cvt_f32_f16_e32 v78, v164
	v_cvt_f32_f16_sdwa v79, v164 dst_sel:DWORD dst_unused:UNUSED_PAD src0_sel:WORD_1
	v_cvt_f32_f16_e32 v80, v165
	v_cvt_f32_f16_sdwa v81, v165 dst_sel:DWORD dst_unused:UNUSED_PAD src0_sel:WORD_1
	v_cvt_f32_f16_e32 v82, v166
	v_cvt_f32_f16_sdwa v83, v166 dst_sel:DWORD dst_unused:UNUSED_PAD src0_sel:WORD_1
	v_cvt_f32_f16_e32 v84, v167
	v_cvt_f32_f16_sdwa v85, v167 dst_sel:DWORD dst_unused:UNUSED_PAD src0_sel:WORD_1
	v_cvt_f32_f16_e32 v86, v168
	v_cvt_f32_f16_sdwa v87, v168 dst_sel:DWORD dst_unused:UNUSED_PAD src0_sel:WORD_1
	v_cvt_f32_f16_e32 v88, v169
	v_cvt_f32_f16_sdwa v89, v169 dst_sel:DWORD dst_unused:UNUSED_PAD src0_sel:WORD_1
	v_cvt_f32_f16_e32 v98, v170
	v_cvt_f32_f16_sdwa v99, v170 dst_sel:DWORD dst_unused:UNUSED_PAD src0_sel:WORD_1
	v_cvt_f32_f16_e32 v90, v171
	v_cvt_f32_f16_sdwa v91, v171 dst_sel:DWORD dst_unused:UNUSED_PAD src0_sel:WORD_1
	v_pk_add_f32 v[2:3], v[156:157], v[62:63]
	global_load_dwordx4 v[100:103], v[22:23], off
	global_load_dwordx4 v[104:107], v[24:25], off
	global_load_dwordx4 v[108:111], v[26:27], off
	global_load_dwordx4 v[112:115], v[28:29], off
	global_load_dwordx4 v[116:119], v[22:23], off offset:1024
	global_load_dwordx4 v[120:123], v[24:25], off offset:1024
	global_load_dwordx4 v[124:127], v[30:31], off
	global_load_dwordx4 v[128:131], v[32:33], off
	global_load_dwordx4 v[132:135], v[22:23], off offset:2048
	global_load_dwordx4 v[136:139], v[24:25], off offset:2048
	global_load_dwordx4 v[140:143], v[34:35], off
	global_load_dwordx4 v[144:147], v[36:37], off
	global_load_dwordx4 v[148:151], v[22:23], off offset:3072
	global_load_dwordx4 v[152:155], v[24:25], off offset:3072
	global_load_dwordx4 v[156:159], v[38:39], off
	global_load_dwordx4 v[160:163], v[40:41], off
	v_pk_add_f32 v[62:63], v[72:73], v[76:77]
	v_pk_add_f32 v[68:69], v[70:71], v[74:75]
	v_pk_add_f32 v[70:71], v[88:89], v[90:91]
	v_pk_add_f32 v[68:69], v[2:3], v[68:69]
	v_pk_add_f32 v[2:3], v[4:5], v[62:63]
	v_pk_add_f32 v[4:5], v[80:81], v[84:85]
	v_pk_add_f32 v[62:63], v[78:79], v[82:83]
	v_pk_add_f32 v[72:73], v[86:87], v[98:99]
	v_pk_add_f32 v[4:5], v[4:5], v[70:71]
	v_pk_add_f32 v[62:63], v[62:63], v[72:73]
	v_pk_add_f32 v[2:3], v[2:3], v[4:5]
	v_pk_add_f32 v[4:5], v[68:69], v[62:63]
	v_mov_b32_e32 v65, v2
	v_mov_b32_e32 v55, v4
	v_mov_b32_e32 v61, v5
	v_mov_b32_e32 v67, v3
	v_pk_add_f32 v[54:55], v[54:55], v[60:61]
	v_pk_add_f32 v[60:61], v[64:65], v[66:67]
	s_nop 0
	v_pk_add_f32 v[54:55], v[54:55], v[60:61]
	s_nop 0
	v_add_f32_e32 v54, v54, v55
	ds_bpermute_b32 v55, v1, v54
	s_waitcnt lgkmcnt(0)
	v_add_f32_e32 v54, v54, v55
	ds_bpermute_b32 v55, v92, v54
	s_waitcnt lgkmcnt(0)
	v_add_f32_e32 v54, v54, v55
	ds_bpermute_b32 v55, v93, v54
	s_waitcnt lgkmcnt(0)
	v_add_f32_e32 v54, v54, v55
	ds_bpermute_b32 v55, v94, v54
	s_waitcnt lgkmcnt(0)
	v_add_f32_e32 v54, v54, v55
	ds_bpermute_b32 v55, v95, v54
	s_waitcnt lgkmcnt(0)
	v_add_f32_e32 v54, v54, v55
	ds_bpermute_b32 v55, v96, v54
	s_waitcnt lgkmcnt(0)
	v_add_f32_e32 v54, v54, v55
	v_fmamk_f32 v60, v54, 0xba800000, v51
	v_fmamk_f32 v62, v54, 0xba800000, v53
	v_fmamk_f32 v55, v54, 0xba800000, v50
	v_fmamk_f32 v61, v54, 0xba800000, v52
	v_mul_f32_e32 v62, v62, v62
	v_mul_f32_e32 v60, v60, v60
	v_fmac_f32_e32 v62, v61, v61
	v_fmac_f32_e32 v60, v55, v55
	v_fmamk_f32 v61, v54, 0xba800000, v47
	v_fmamk_f32 v63, v54, 0xba800000, v49
	v_add_f32_e32 v55, v62, v60
	v_fmamk_f32 v60, v54, 0xba800000, v46
	v_fmamk_f32 v62, v54, 0xba800000, v48
	v_mul_f32_e32 v63, v63, v63
	v_mul_f32_e32 v61, v61, v61
	v_fmac_f32_e32 v63, v62, v62
	v_fmac_f32_e32 v61, v60, v60
	v_add_f32_e32 v60, v63, v61
	v_fmamk_f32 v61, v54, 0xba800000, v57
	v_fmamk_f32 v63, v54, 0xba800000, v59
	v_add_f32_e32 v55, v55, v60
	v_fmamk_f32 v60, v54, 0xba800000, v56
	v_fmamk_f32 v62, v54, 0xba800000, v58
	v_mul_f32_e32 v63, v63, v63
	v_mul_f32_e32 v61, v61, v61
	v_fmac_f32_e32 v63, v62, v62
	v_fmac_f32_e32 v61, v60, v60
	v_add_f32_e32 v60, v63, v61
	v_fmamk_f32 v61, v54, 0xba800000, v3
	v_fmamk_f32 v63, v54, 0xba800000, v5
	v_add_f32_e32 v55, v60, v55
	v_fmamk_f32 v60, v54, 0xba800000, v2
	v_fmamk_f32 v62, v54, 0xba800000, v4
	v_mul_f32_e32 v63, v63, v63
	v_mul_f32_e32 v61, v61, v61
	v_fmac_f32_e32 v63, v62, v62
	v_fmac_f32_e32 v61, v60, v60
	v_add_f32_e32 v60, v63, v61
	v_add_f32_e32 v55, v60, v55
	ds_bpermute_b32 v60, v1, v55
	s_waitcnt lgkmcnt(0)
	v_add_f32_e32 v55, v55, v60
	ds_bpermute_b32 v60, v92, v55
	s_waitcnt lgkmcnt(0)
	v_add_f32_e32 v55, v55, v60
	ds_bpermute_b32 v60, v93, v55
	s_waitcnt lgkmcnt(0)
	v_add_f32_e32 v55, v55, v60
	ds_bpermute_b32 v60, v94, v55
	s_waitcnt lgkmcnt(0)
	v_add_f32_e32 v55, v55, v60
	ds_bpermute_b32 v60, v95, v55
	s_waitcnt lgkmcnt(0)
	v_add_f32_e32 v55, v55, v60
	ds_bpermute_b32 v60, v96, v55
	s_and_saveexec_b64 s[12:13], s[38:39]
	s_cbranch_execz .LBB0_1924
	v_mul_f32_e32 v54, 0x3a800000, v54
	s_waitcnt lgkmcnt(0)
	v_add_f32_e32 v55, v55, v60
	v_mov_b32_e32 v60, s22
	ds_write_b64 v60, v[54:55]
; #define GAS __attribute__((address_space(1)))
; __device__ __forceinline__ unsigned pk2(float lo, float hi) { unsigned r; asm("v_cvt_pk_bf16_f32 %0, %1, %2" : "=v"(r) : "v"(lo), "v"(hi)); return r; }
; __device__ __forceinline__ void ln_phase(Frame& F, CArgs a, int l, int which) {
;     ...
;         __syncthreads();
;         const f32x2v s0 = XS[p], s1 = XS[p + 4];
;         const float mean = 0.5f * (s0.x + s1.x), d0 = s0.x - mean, d1 = s1.x - mean;
;         const float rstd = 1.0f / sqrtf(((s0.y + s1.y) + 1024.0f * (d0 * d0 + d1 * d1)) * (1.0f / D) + LN_EPS);
;         if (!valid) continue;
;         const GAS float* sh = mod + (size_t)3 * 12288; const GAS float* sc = sh + D;
;         GAS f16_t* xo = X + (size_t)row * D;
;         GAS u32x2* xm = (GAS u32x2*)(XM + (size_t)row * D);
; #pragma unroll
;         for (int j = 0; j < 4; ++j) { const int i4 = lane + 64 * (j + 4 * half); const f32x4 y = (v[j] - mean) * rstd * ((const GAS f32x4*)g)[i4] + ((const GAS f32x4*)bb)[i4];
;             stx4(xo + i4 * 4, y);
;             const f32x4 r = y * (((const GAS f32x4*)sc)[i4] + 1.0f) + ((const GAS f32x4*)sh)[i4]; u32x2 w; w.x = pk2(r[0], r[1]); w.y = pk2(r[2], r[3]); xm[i4] = w; }
.LBB0_1924:
	s_or_b64 exec, exec, s[12:13]
	s_andn2_b64 vcc, exec, s[10:11]
	s_waitcnt lgkmcnt(0)
	s_barrier
	s_cbranch_vccnz .LBB0_1921
	v_mov_b32_e32 v54, s19
	ds_read2_b64 v[60:63], v54 offset1:4
	s_mov_b32 s10, 0xf800000
	s_lshl_b64 s[8:9], s[8:9], 11
	s_waitcnt lgkmcnt(0)
	v_add_f32_e32 v55, v60, v62
	v_fma_f32 v54, -0.5, v55, v60
	v_mul_f32_e32 v65, v54, v54
	v_fma_f32 v54, -0.5, v55, v62
	v_mul_f32_e32 v67, v54, v54
	v_mov_b32_e32 v64, v61
	v_mov_b32_e32 v66, v63
	v_pk_add_f32 v[60:61], v[64:65], v[66:67]
	v_fma_f32 v51, -0.5, v55, v51
	v_fmac_f32_e32 v60, 0x44800000, v61
	v_fmamk_f32 v54, v60, 0x3a000000, v230
	v_cmp_gt_f32_e32 vcc, s10, v54
	v_mul_f32_e32 v60, 0x4f800000, v54
	v_fmac_f32_e32 v50, -0.5, v55
	v_cndmask_b32_e32 v54, v54, v60, vcc
	v_sqrt_f32_e32 v60, v54
	v_fma_f32 v53, -0.5, v55, v53
	v_fmac_f32_e32 v52, -0.5, v55
	v_fma_f32 v47, -0.5, v55, v47
	v_add_u32_e32 v61, -1, v60
	v_fma_f32 v62, -v61, v60, v54
	v_cmp_ge_f32_e64 s[40:41], 0, v62
	v_add_u32_e32 v62, 1, v60
	v_fmac_f32_e32 v46, -0.5, v55
	v_cndmask_b32_e64 v61, v60, v61, s[40:41]
	v_fma_f32 v60, -v62, v60, v54
	v_cmp_lt_f32_e64 s[40:41], 0, v60
	v_fma_f32 v49, -0.5, v55, v49
	v_fmac_f32_e32 v48, -0.5, v55
	v_cndmask_b32_e64 v60, v61, v62, s[40:41]
	v_mul_f32_e32 v61, 0x37800000, v60
	v_cndmask_b32_e32 v60, v60, v61, vcc
	v_cmp_class_f32_e32 vcc, v54, v229
	v_fma_f32 v57, -0.5, v55, v57
	v_fmac_f32_e32 v56, -0.5, v55
	v_cndmask_b32_e32 v54, v60, v54, vcc
	v_div_scale_f32 v60, s[10:11], v54, v54, 1.0
	v_rcp_f32_e32 v61, v60
	s_lshl_b64 s[10:11], s[8:9], 1
	s_add_u32 s8, s4, s10
	s_addc_u32 s9, s5, s11
	v_fma_f32 v62, -v60, v61, 1.0
	v_fmac_f32_e32 v61, v62, v61
	v_div_scale_f32 v62, vcc, 1.0, v54, 1.0
	v_mul_f32_e32 v63, v62, v61
	v_fma_f32 v64, -v60, v63, v62
	v_fmac_f32_e32 v63, v64, v61
	v_fma_f32 v60, -v60, v63, v62
	v_div_fmas_f32 v60, v60, v61, v63
	v_div_fixup_f32 v54, v60, v54, 1.0
	v_pk_mul_f32 v[64:65], v[52:53], v[54:55] op_sel_hi:[1,0]
	v_pk_mul_f32 v[66:67], v[50:51], v[54:55] op_sel_hi:[1,0]
	v_fma_f32 v59, -0.5, v55, v59
	v_fmac_f32_e32 v58, -0.5, v55
	v_fma_f32 v3, -0.5, v55, v3
	v_fmac_f32_e32 v2, -0.5, v55
	v_fma_f32 v5, -0.5, v55, v5
	v_fmac_f32_e32 v4, -0.5, v55
	s_waitcnt vmcnt(0)
	v_pk_fma_f32 v[62:63], v[102:103], v[66:67], v[106:107]
	v_pk_fma_f32 v[60:61], v[100:101], v[64:65], v[104:105]
	v_med3_f32 v53, v62, s84, v245
	v_med3_f32 v52, v60, s84, v245
	v_med3_f32 v64, v61, s84, v245
	v_med3_f32 v65, v63, s84, v245
	v_lshl_add_u64 v[50:51], v[6:7], 1, s[8:9]
	v_cvt_pk_f16_f32 v53, v53, v65
	v_cvt_pk_f16_f32 v52, v52, v64
	global_store_dwordx2 v[50:51], v[52:53], off
	v_pk_add_f32 v[64:65], v[110:111], 1.0 op_sel_hi:[1,0]
	v_pk_add_f32 v[66:67], v[108:109], 1.0 op_sel_hi:[1,0]
	v_pk_fma_f32 v[50:51], v[66:67], v[60:61], v[112:113]
	s_nop 0
	v_cvt_pk_bf16_f32 v60, v50, v51
	v_lshl_add_u64 v[50:51], v[44:45], 0, s[10:11]
	v_pk_fma_f32 v[52:53], v[64:65], v[62:63], v[114:115]
	v_pk_mul_f32 v[64:65], v[46:47], v[54:55] op_sel_hi:[1,0]
	v_cvt_pk_bf16_f32 v61, v52, v53
	global_store_dwordx2 v[50:51], v[60:61], off
	v_pk_mul_f32 v[52:53], v[48:49], v[54:55] op_sel_hi:[1,0]
	v_pk_fma_f32 v[62:63], v[118:119], v[64:65], v[122:123]
	v_pk_fma_f32 v[52:53], v[116:117], v[52:53], v[120:121]
	v_med3_f32 v60, v62, s84, v245
	v_med3_f32 v48, v52, s84, v245
	v_med3_f32 v49, v53, s84, v245
	v_med3_f32 v61, v63, s84, v245
	v_lshl_add_u64 v[46:47], v[10:11], 1, s[8:9]
	v_cvt_pk_f16_f32 v48, v48, v49
	v_cvt_pk_f16_f32 v49, v60, v61
	global_store_dwordx2 v[46:47], v[48:49], off
	v_pk_add_f32 v[60:61], v[126:127], 1.0 op_sel_hi:[1,0]
	v_pk_add_f32 v[64:65], v[124:125], 1.0 op_sel_hi:[1,0]
	v_pk_fma_f32 v[46:47], v[64:65], v[52:53], v[128:129]
	v_pk_fma_f32 v[48:49], v[60:61], v[62:63], v[130:131]
	v_cvt_pk_bf16_f32 v46, v46, v47
	v_pk_mul_f32 v[52:53], v[58:59], v[54:55] op_sel_hi:[1,0]
	v_cvt_pk_bf16_f32 v47, v48, v49
	global_store_dwordx2 v[50:51], v[46:47], off offset:512
	v_pk_mul_f32 v[60:61], v[56:57], v[54:55] op_sel_hi:[1,0]
	v_pk_fma_f32 v[58:59], v[60:61], v[134:135], v[138:139]
	v_pk_fma_f32 v[52:53], v[52:53], v[132:133], v[136:137]
	v_med3_f32 v56, v58, s84, v245
	v_med3_f32 v48, v52, s84, v245
	v_med3_f32 v49, v53, s84, v245
	v_med3_f32 v57, v59, s84, v245
	v_lshl_add_u64 v[46:47], v[14:15], 1, s[8:9]
	v_cvt_pk_f16_f32 v48, v48, v49
	v_cvt_pk_f16_f32 v49, v56, v57
	global_store_dwordx2 v[46:47], v[48:49], off
	v_pk_add_f32 v[56:57], v[142:143], 1.0 op_sel_hi:[1,0]
	v_pk_add_f32 v[60:61], v[140:141], 1.0 op_sel_hi:[1,0]
	v_pk_fma_f32 v[46:47], v[52:53], v[60:61], v[144:145]
	v_pk_fma_f32 v[48:49], v[58:59], v[56:57], v[146:147]
	v_cvt_pk_bf16_f32 v46, v46, v47
	v_pk_mul_f32 v[52:53], v[4:5], v[54:55] op_sel_hi:[1,0]
	v_cvt_pk_bf16_f32 v47, v48, v49
	global_store_dwordx2 v[50:51], v[46:47], off offset:1024
	v_pk_mul_f32 v[54:55], v[2:3], v[54:55] op_sel_hi:[1,0]
	v_pk_fma_f32 v[48:49], v[54:55], v[150:151], v[154:155]
	v_pk_fma_f32 v[46:47], v[52:53], v[148:149], v[152:153]
	v_med3_f32 v52, v48, s84, v245
	v_med3_f32 v4, v46, s84, v245
	v_med3_f32 v5, v47, s84, v245
	v_med3_f32 v53, v49, s84, v245
	v_lshl_add_u64 v[2:3], v[18:19], 1, s[8:9]
	v_cvt_pk_f16_f32 v4, v4, v5
	v_cvt_pk_f16_f32 v5, v52, v53
	global_store_dwordx2 v[2:3], v[4:5], off
	v_pk_add_f32 v[52:53], v[158:159], 1.0 op_sel_hi:[1,0]
	v_pk_add_f32 v[54:55], v[156:157], 1.0 op_sel_hi:[1,0]
	v_pk_fma_f32 v[2:3], v[46:47], v[54:55], v[160:161]
	v_pk_fma_f32 v[4:5], v[48:49], v[52:53], v[162:163]
	v_cvt_pk_bf16_f32 v2, v2, v3
	s_nop 0
	v_cvt_pk_bf16_f32 v3, v4, v5
	global_store_dwordx2 v[50:51], v[2:3], off offset:1536
	s_branch .LBB0_1921
